# v_m3 + safety net: a block whose queue fetch runs past the end tries the scan counter before leaving (all scan items run under any TG_ID behaviour)
# baseline (speedup 1.0000x reference)
; DI void phase_attn_scan(const Params& p, int l, int half, char* smem, int rep) {
;     ...
;   for (;;) {
;     __syncthreads();
;     if (threadIdx.x == 0) s_item = (int)atomicAdd(cnt, 1u);
;     __syncthreads();
;     int it = s_item;
;     if (it >= total) break;
;     if (it < n_scan) { scan_item(p, it, smem); continue; }
.LBB0_161:
	s_or_b64 exec, exec, s[12:13]
	s_waitcnt vmcnt(0)
	v_readfirstlane_b32 s12, v1
	s_nop 1
	v_add_u32_e32 v0, s12, v0
	v_add_u32_e32 v0, 0x80, v0
	v_cmp_le_i32_e32 vcc, s69, v0
	s_cbranch_vccz .Lq_store
	v_readlane_b32 s36, v255, 23
	v_readlane_b32 s37, v255, 24
	v_mov_b32_e32 v1, 1
	s_nop 4
	global_atomic_add v1, v177, v1, s[36:37] offset:128 sc0
	s_waitcnt vmcnt(0)
	v_cmp_gt_u32_e32 vcc, 0x80, v1
	s_nop 1
	v_cndmask_b32_e32 v0, v0, v1, vcc
.Lq_store:
	ds_write_b32 v200, v0
